# E10 + V^T buffer of mixer A re-laid out so that 4 consecutive lanes read 64 contiguous bytes (writer ft==0 + mixer A loop loads)
# baseline (speedup 1.0000x reference)
;     __device__ __forceinline__ void operator()(const f32x4 (&acc)[2][2][4][2], const Unit& u, int wr, int wc, int fr, int fq) const {
;     ...
;         if (u.kind == 1) {
;             const int ft = u.pm, tt = u.pn; bf16_t* base; int fbase, ai_lo = 0;
;             if (ft == 0) { base = VTA; fbase = -128; ai_lo = 1; } else if (ft < 3) { base = VTB; fbase = (ft - 1) * 256; } else { base = VTD; fbase = (ft - 3) * 256; }
;             for (int ai = ai_lo; ai < 2; ++ai)
.LBB0_289:
	s_cmp_lg_u32 s18, 0
	s_cselect_b64 s[56:57], -1, 0
	s_cmp_eq_u32 s18, 0
	s_cbranch_scc1 .LBB0_296
	s_lshl_b32 s37, s18, 8
	s_cmp_gt_i32 s18, 2
	s_mov_b64 s[4:5], -1
	s_cbranch_scc0 .LBB0_292
	s_mov_b32 s99, 0
	s_add_i32 s7, s37, 0xfffffd00
	s_mov_b64 s[4:5], 0
.LBB0_292:
	s_andn2_b64 vcc, exec, s[4:5]
	s_mov_b64 s[4:5], s[30:31]
	s_cbranch_vccnz .LBB0_294
	s_mov_b32 s99, 0
	v_readlane_b32 s4, v255, 55
	s_add_i32 s7, s37, 0xffffff00
	v_readlane_b32 s5, v255, 56

; __host__ __device__ __forceinline__ int vt_off(int d, int p) { return (d >> 1) * VTPP + (p >> 5) * 64 + (d & 1) * 32 + (p & 31); }
; __device__ __forceinline__ unsigned cvt_pk_bf16(float lo, float hi) { f32x2_c v = {lo, hi}; bf16x2_c b = __builtin_convertvector(v, bf16x2_c); return __builtin_bit_cast(unsigned, b); }
;     __device__ __forceinline__ void operator()(const f32x4 (&acc)[2][2][4][2], const Unit& u, int wr, int wc, int fr, int fq) const {
;     ...
;             if (ft == 0) { base = VTA; fbase = -128; ai_lo = 1; } else if (ft < 3) { base = VTB; fbase = (ft - 1) * 256; } else { base = VTD; fbase = (ft - 3) * 256; }
;             for (int ai = ai_lo; ai < 2; ++ai)
; #pragma unroll
;                 for (int m = 0; m < 4; ++m) { bf16_t* rowp = base + vt_off(fbase + 128 * ai + 64 * wr + 16 * m + fr, 256 * tt + 32 * wc + 8 * fq);
; #pragma unroll
;                     for (int bj = 0; bj < 2; ++bj) { const f32x4 v0 = ai ? acc[1][bj][m][0] : acc[0][bj][m][0], v1 = ai ? acc[1][bj][m][1] : acc[0][bj][m][1];
;                         u32x4 w; w.x = cvt_pk_bf16(v0[0], v0[1]); w.y = cvt_pk_bf16(v0[2], v0[3]); w.z = cvt_pk_bf16(v1[0], v1[1]); w.w = cvt_pk_bf16(v1[2], v1[3]);
;                         *(u32x4*)(rowp + bj * 256) = w; } }
.LBB0_296:
	s_mov_b32 s99, 1
	v_mov_b64_e32 v[70:71], v[6:7]
	v_mov_b64_e32 v[94:95], v[10:11]
	v_mov_b64_e32 v[66:67], v[2:3]
	v_mov_b64_e32 v[102:103], v[22:23]
	v_mov_b64_e32 v[78:79], v[18:19]
	v_mov_b64_e32 v[106:107], v[30:31]
	v_mov_b64_e32 v[74:75], v[14:15]
	v_mov_b64_e32 v[110:111], v[42:43]
	v_mov_b64_e32 v[86:87], v[34:35]
	v_mov_b64_e32 v[114:115], v[50:51]
	v_mov_b64_e32 v[82:83], v[26:27]
	v_mov_b64_e32 v[118:119], v[54:55]
	v_mov_b64_e32 v[98:99], v[46:47]
	v_mov_b64_e32 v[122:123], v[58:59]
	v_mov_b64_e32 v[90:91], v[38:39]
	v_mov_b64_e32 v[126:127], v[62:63]
	s_movk_i32 s7, 0xff80
	s_movk_i32 s18, 0x80
	v_mov_b64_e32 v[68:69], v[4:5]
	v_mov_b64_e32 v[92:93], v[8:9]
	v_mov_b64_e32 v[64:65], v[0:1]
	v_mov_b64_e32 v[100:101], v[20:21]
	v_mov_b64_e32 v[76:77], v[16:17]
	v_mov_b64_e32 v[104:105], v[28:29]
	v_mov_b64_e32 v[72:73], v[12:13]
	v_mov_b64_e32 v[108:109], v[40:41]
	v_mov_b64_e32 v[84:85], v[32:33]
	v_mov_b64_e32 v[112:113], v[48:49]
	v_mov_b64_e32 v[80:81], v[24:25]
	v_mov_b64_e32 v[116:117], v[52:53]
	v_mov_b64_e32 v[96:97], v[44:45]
	v_mov_b64_e32 v[120:121], v[56:57]
	v_mov_b64_e32 v[88:89], v[36:37]
	v_mov_b64_e32 v[124:125], v[60:61]
	s_mov_b64 s[4:5], s[26:27]
.LBB0_297:
	s_cmp_lg_u32 s99, 0
	s_cbranch_scc1 .Lvt_new
	s_add_i32 s7, s7, s28
	v_add_u32_e32 v129, s7, v175
	s_lshl_b32 s7, s16, 9
	s_or_b32 s7, s7, s81
	v_lshlrev_b32_e32 v128, 3, v173
	v_lshl_add_u32 v130, v173, 4, s7
	v_lshlrev_b32_e32 v131, 5, v129
	v_and_b32_e32 v130, 0xffffffc0, v130
	v_and_b32_e32 v128, 24, v128
	v_and_b32_e32 v131, 32, v131
	v_add_u32_e32 v132, s18, v129
	v_or3_b32 v128, v130, v128, v131
	v_lshrrev_b32_e32 v130, 1, v132
	v_mad_u64_u32 v[130:131], s[62:63], v130, s65, v[128:129]
	v_ashrrev_i32_e32 v131, 31, v130
	v_lshl_add_u64 v[130:131], v[130:131], 1, s[4:5]
	v_cvt_pk_bf16_f32 v124, v124, v125
	v_cvt_pk_bf16_f32 v125, v126, v127
	v_cvt_pk_bf16_f32 v126, v88, v89
	v_cvt_pk_bf16_f32 v127, v90, v91
	v_cvt_pk_bf16_f32 v88, v120, v121
	v_cvt_pk_bf16_f32 v89, v122, v123
	v_cvt_pk_bf16_f32 v90, v96, v97
	v_cvt_pk_bf16_f32 v91, v98, v99
	global_store_dwordx4 v[130:131], v[88:91], off offset:512
	global_store_dwordx4 v[130:131], v[124:127], off
	s_andn2_b64 vcc, exec, s[56:57]
	v_add_u32_e32 v88, 16, v132
	v_lshrrev_b32_e32 v88, 1, v88
	v_mad_u64_u32 v[88:89], s[62:63], v88, s65, v[128:129]
	v_ashrrev_i32_e32 v89, 31, v88
	v_lshl_add_u64 v[96:97], v[88:89], 1, s[4:5]
	v_cvt_pk_bf16_f32 v90, v80, v81
	v_cvt_pk_bf16_f32 v91, v82, v83
	v_cvt_pk_bf16_f32 v80, v112, v113
	v_cvt_pk_bf16_f32 v81, v114, v115
	v_cvt_pk_bf16_f32 v82, v84, v85
	v_cvt_pk_bf16_f32 v83, v86, v87
	global_store_dwordx4 v[96:97], v[80:83], off offset:512
	v_cvt_pk_bf16_f32 v88, v116, v117
	v_cvt_pk_bf16_f32 v89, v118, v119
	v_add_u32_e32 v80, 32, v132
	v_lshrrev_b32_e32 v80, 1, v80
	v_mad_u64_u32 v[80:81], s[62:63], v80, s65, v[128:129]
	v_ashrrev_i32_e32 v81, 31, v80
	v_lshl_add_u64 v[84:85], v[80:81], 1, s[4:5]
	v_cvt_pk_bf16_f32 v82, v72, v73
	v_cvt_pk_bf16_f32 v83, v74, v75
	v_cvt_pk_bf16_f32 v72, v104, v105
	v_cvt_pk_bf16_f32 v73, v106, v107
	v_cvt_pk_bf16_f32 v74, v76, v77
	v_cvt_pk_bf16_f32 v75, v78, v79
	global_store_dwordx4 v[96:97], v[88:91], off
	global_store_dwordx4 v[84:85], v[72:75], off offset:512
	v_cvt_pk_bf16_f32 v80, v108, v109
	v_cvt_pk_bf16_f32 v81, v110, v111
	v_add_u32_e32 v72, 48, v132
	v_lshrrev_b32_e32 v72, 1, v72
	v_mad_u64_u32 v[72:73], s[62:63], v72, s65, v[128:129]
	v_ashrrev_i32_e32 v73, 31, v72
	v_lshl_add_u64 v[76:77], v[72:73], 1, s[4:5]
	v_cvt_pk_bf16_f32 v72, v100, v101
	v_cvt_pk_bf16_f32 v73, v102, v103
	v_cvt_pk_bf16_f32 v74, v64, v65
	v_cvt_pk_bf16_f32 v75, v66, v67
	v_cvt_pk_bf16_f32 v64, v92, v93
	v_cvt_pk_bf16_f32 v65, v94, v95
	v_cvt_pk_bf16_f32 v66, v68, v69
	v_cvt_pk_bf16_f32 v67, v70, v71
	global_store_dwordx4 v[84:85], v[80:83], off
	global_store_dwordx4 v[76:77], v[72:75], off
	global_store_dwordx4 v[76:77], v[64:67], off offset:512
	s_cbranch_vccnz .LBB0_299
	s_nop 0
	v_add_u32_e32 v64, 0x80, v129
	v_lshrrev_b32_e32 v64, 1, v64
	v_mad_u64_u32 v[64:65], s[56:57], v64, s65, v[128:129]
	v_ashrrev_i32_e32 v65, 31, v64
	v_lshl_add_u64 v[64:65], v[64:65], 1, s[4:5]
	v_cvt_pk_bf16_f32 v60, v60, v61
	v_cvt_pk_bf16_f32 v61, v62, v63
	v_cvt_pk_bf16_f32 v62, v36, v37
	v_cvt_pk_bf16_f32 v63, v38, v39
	v_cvt_pk_bf16_f32 v36, v56, v57
	v_cvt_pk_bf16_f32 v37, v58, v59
	v_cvt_pk_bf16_f32 v38, v44, v45
	v_cvt_pk_bf16_f32 v39, v46, v47
	global_store_dwordx4 v[64:65], v[36:39], off offset:512
	global_store_dwordx4 v[64:65], v[60:63], off
	s_nop 0
	v_add_u32_e32 v36, 0x90, v129
	v_lshrrev_b32_e32 v36, 1, v36
	v_mad_u64_u32 v[36:37], s[56:57], v36, s65, v[128:129]
	v_ashrrev_i32_e32 v37, 31, v36
	v_lshl_add_u64 v[44:45], v[36:37], 1, s[4:5]
	v_cvt_pk_bf16_f32 v38, v24, v25
	v_cvt_pk_bf16_f32 v39, v26, v27
	v_cvt_pk_bf16_f32 v24, v48, v49
	v_cvt_pk_bf16_f32 v25, v50, v51
	v_cvt_pk_bf16_f32 v26, v32, v33
	v_cvt_pk_bf16_f32 v27, v34, v35
	global_store_dwordx4 v[44:45], v[24:27], off offset:512
	v_cvt_pk_bf16_f32 v36, v52, v53
	v_cvt_pk_bf16_f32 v37, v54, v55
	v_add_u32_e32 v24, 0xa0, v129
	v_lshrrev_b32_e32 v24, 1, v24
	v_mad_u64_u32 v[24:25], s[56:57], v24, s65, v[128:129]
	v_ashrrev_i32_e32 v25, 31, v24
	v_lshl_add_u64 v[32:33], v[24:25], 1, s[4:5]
	v_cvt_pk_bf16_f32 v26, v12, v13
	v_cvt_pk_bf16_f32 v27, v14, v15
	v_cvt_pk_bf16_f32 v12, v28, v29
	v_cvt_pk_bf16_f32 v13, v30, v31
	v_cvt_pk_bf16_f32 v14, v16, v17
	v_cvt_pk_bf16_f32 v15, v18, v19
	global_store_dwordx4 v[44:45], v[36:39], off
	global_store_dwordx4 v[32:33], v[12:15], off offset:512
	v_cvt_pk_bf16_f32 v24, v40, v41
	v_cvt_pk_bf16_f32 v25, v42, v43
	v_add_u32_e32 v12, 0xb0, v129
	v_lshrrev_b32_e32 v12, 1, v12
	v_mad_u64_u32 v[12:13], s[56:57], v12, s65, v[128:129]
	v_ashrrev_i32_e32 v13, 31, v12
	v_lshl_add_u64 v[16:17], v[12:13], 1, s[4:5]
	v_cvt_pk_bf16_f32 v12, v20, v21
	v_cvt_pk_bf16_f32 v13, v22, v23
	v_cvt_pk_bf16_f32 v14, v0, v1
	v_cvt_pk_bf16_f32 v15, v2, v3
	v_cvt_pk_bf16_f32 v0, v8, v9
	v_cvt_pk_bf16_f32 v1, v10, v11
	v_cvt_pk_bf16_f32 v2, v4, v5
	v_cvt_pk_bf16_f32 v3, v6, v7
	global_store_dwordx4 v[32:33], v[24:27], off
	global_store_dwordx4 v[16:17], v[12:15], off
	global_store_dwordx4 v[16:17], v[0:3], off offset:512
	s_branch .LBB0_299
; __device__ __forceinline__ unsigned cvt_pk_bf16(float lo, float hi) { f32x2_c v = {lo, hi}; bf16x2_c b = __builtin_convertvector(v, bf16x2_c); return __builtin_bit_cast(unsigned, b); }
; __host__ __device__ __forceinline__ int vt_off(int d, int p) { return (d >> 1) * VTPP + (p >> 5) * 64 + (d & 1) * 32 + (p & 31); }
;     __device__ __forceinline__ void operator()(const f32x4 (&acc)[2][2][4][2], const Unit& u, int wr, int wc, int fr, int fq) const {
;     ...
;             for (int ai = ai_lo; ai < 2; ++ai)
; #pragma unroll
;                 for (int m = 0; m < 4; ++m) { bf16_t* rowp = base + vt_off(fbase + 128 * ai + 64 * wr + 16 * m + fr, 256 * tt + 32 * wc + 8 * fq);
; #pragma unroll
;                     for (int bj = 0; bj < 2; ++bj) { const f32x4 v0 = ai ? acc[1][bj][m][0] : acc[0][bj][m][0], v1 = ai ? acc[1][bj][m][1] : acc[0][bj][m][1];
;                         u32x4 w; w.x = cvt_pk_bf16(v0[0], v0[1]); w.y = cvt_pk_bf16(v0[2], v0[3]); w.z = cvt_pk_bf16(v1[0], v1[1]); w.w = cvt_pk_bf16(v1[2], v1[3]);
;                         *(u32x4*)(rowp + bj * 256) = w; } }
.Lvt_new:
	s_mov_b32 s98, 0x10080
	s_add_i32 s7, s7, s28
	v_add_u32_e32 v129, s7, v175
	s_lshl_b32 s7, s16, 9
	s_or_b32 s7, s7, s81
	v_lshlrev_b32_e32 v128, 5, v173
	v_lshl_add_u32 v130, v173, 4, s7
	v_lshlrev_b32_e32 v131, 3, v129
	v_and_b32_e32 v130, 0xffffffc0, v130
	v_lshlrev_b32_e32 v130, 1, v130
	v_and_b32_e32 v128, 0x60, v128
	v_and_b32_e32 v131, 24, v131
	v_add_u32_e32 v132, s18, v129
	v_or3_b32 v128, v130, v128, v131
	v_lshrrev_b32_e32 v130, 2, v132
	v_mad_u64_u32 v[130:131], s[62:63], v130, s98, v[128:129]
	v_ashrrev_i32_e32 v131, 31, v130
	v_lshl_add_u64 v[130:131], v[130:131], 1, s[4:5]
	v_cvt_pk_bf16_f32 v124, v124, v125
	v_cvt_pk_bf16_f32 v125, v126, v127
	v_cvt_pk_bf16_f32 v126, v88, v89
	v_cvt_pk_bf16_f32 v127, v90, v91
	v_cvt_pk_bf16_f32 v88, v120, v121
	v_cvt_pk_bf16_f32 v89, v122, v123
	v_cvt_pk_bf16_f32 v90, v96, v97
	v_cvt_pk_bf16_f32 v91, v98, v99
	global_store_dwordx4 v[130:131], v[88:91], off offset:1024
	global_store_dwordx4 v[130:131], v[124:127], off
	s_andn2_b64 vcc, exec, s[56:57]
	v_add_u32_e32 v88, 16, v132
	v_lshrrev_b32_e32 v88, 2, v88
	v_mad_u64_u32 v[88:89], s[62:63], v88, s98, v[128:129]
	v_ashrrev_i32_e32 v89, 31, v88
	v_lshl_add_u64 v[96:97], v[88:89], 1, s[4:5]
	v_cvt_pk_bf16_f32 v90, v80, v81
	v_cvt_pk_bf16_f32 v91, v82, v83
	v_cvt_pk_bf16_f32 v80, v112, v113
	v_cvt_pk_bf16_f32 v81, v114, v115
	v_cvt_pk_bf16_f32 v82, v84, v85
	v_cvt_pk_bf16_f32 v83, v86, v87
	global_store_dwordx4 v[96:97], v[80:83], off offset:1024
	v_cvt_pk_bf16_f32 v88, v116, v117
	v_cvt_pk_bf16_f32 v89, v118, v119
	v_add_u32_e32 v80, 32, v132
	v_lshrrev_b32_e32 v80, 2, v80
	v_mad_u64_u32 v[80:81], s[62:63], v80, s98, v[128:129]
	v_ashrrev_i32_e32 v81, 31, v80
	v_lshl_add_u64 v[84:85], v[80:81], 1, s[4:5]
	v_cvt_pk_bf16_f32 v82, v72, v73
	v_cvt_pk_bf16_f32 v83, v74, v75
	v_cvt_pk_bf16_f32 v72, v104, v105
	v_cvt_pk_bf16_f32 v73, v106, v107
	v_cvt_pk_bf16_f32 v74, v76, v77
	v_cvt_pk_bf16_f32 v75, v78, v79
	global_store_dwordx4 v[96:97], v[88:91], off
	global_store_dwordx4 v[84:85], v[72:75], off offset:1024
	v_cvt_pk_bf16_f32 v80, v108, v109
	v_cvt_pk_bf16_f32 v81, v110, v111
	v_add_u32_e32 v72, 48, v132
	v_lshrrev_b32_e32 v72, 2, v72
	v_mad_u64_u32 v[72:73], s[62:63], v72, s98, v[128:129]
	v_ashrrev_i32_e32 v73, 31, v72
	v_lshl_add_u64 v[76:77], v[72:73], 1, s[4:5]
	v_cvt_pk_bf16_f32 v72, v100, v101
	v_cvt_pk_bf16_f32 v73, v102, v103
	v_cvt_pk_bf16_f32 v74, v64, v65
	v_cvt_pk_bf16_f32 v75, v66, v67
	v_cvt_pk_bf16_f32 v64, v92, v93
	v_cvt_pk_bf16_f32 v65, v94, v95
	v_cvt_pk_bf16_f32 v66, v68, v69
	v_cvt_pk_bf16_f32 v67, v70, v71
	global_store_dwordx4 v[84:85], v[80:83], off
	global_store_dwordx4 v[76:77], v[72:75], off
	global_store_dwordx4 v[76:77], v[64:67], off offset:1024
	s_cbranch_vccnz .LBB0_299
	s_nop 0
	v_add_u32_e32 v64, 0x80, v129
	v_lshrrev_b32_e32 v64, 2, v64
	v_mad_u64_u32 v[64:65], s[56:57], v64, s98, v[128:129]
	v_ashrrev_i32_e32 v65, 31, v64
	v_lshl_add_u64 v[64:65], v[64:65], 1, s[4:5]
	v_cvt_pk_bf16_f32 v60, v60, v61
	v_cvt_pk_bf16_f32 v61, v62, v63
	v_cvt_pk_bf16_f32 v62, v36, v37
	v_cvt_pk_bf16_f32 v63, v38, v39
	v_cvt_pk_bf16_f32 v36, v56, v57
	v_cvt_pk_bf16_f32 v37, v58, v59
	v_cvt_pk_bf16_f32 v38, v44, v45
	v_cvt_pk_bf16_f32 v39, v46, v47
	global_store_dwordx4 v[64:65], v[36:39], off offset:1024
	global_store_dwordx4 v[64:65], v[60:63], off
	s_nop 0
	v_add_u32_e32 v36, 0x90, v129
	v_lshrrev_b32_e32 v36, 2, v36
	v_mad_u64_u32 v[36:37], s[56:57], v36, s98, v[128:129]
	v_ashrrev_i32_e32 v37, 31, v36
	v_lshl_add_u64 v[44:45], v[36:37], 1, s[4:5]
	v_cvt_pk_bf16_f32 v38, v24, v25
	v_cvt_pk_bf16_f32 v39, v26, v27
	v_cvt_pk_bf16_f32 v24, v48, v49
	v_cvt_pk_bf16_f32 v25, v50, v51
	v_cvt_pk_bf16_f32 v26, v32, v33
	v_cvt_pk_bf16_f32 v27, v34, v35
	global_store_dwordx4 v[44:45], v[24:27], off offset:1024
	v_cvt_pk_bf16_f32 v36, v52, v53
	v_cvt_pk_bf16_f32 v37, v54, v55
	v_add_u32_e32 v24, 0xa0, v129
	v_lshrrev_b32_e32 v24, 2, v24
	v_mad_u64_u32 v[24:25], s[56:57], v24, s98, v[128:129]
	v_ashrrev_i32_e32 v25, 31, v24
	v_lshl_add_u64 v[32:33], v[24:25], 1, s[4:5]
	v_cvt_pk_bf16_f32 v26, v12, v13
	v_cvt_pk_bf16_f32 v27, v14, v15
	v_cvt_pk_bf16_f32 v12, v28, v29
	v_cvt_pk_bf16_f32 v13, v30, v31
	v_cvt_pk_bf16_f32 v14, v16, v17
	v_cvt_pk_bf16_f32 v15, v18, v19
	global_store_dwordx4 v[44:45], v[36:39], off
	global_store_dwordx4 v[32:33], v[12:15], off offset:1024
	v_cvt_pk_bf16_f32 v24, v40, v41
	v_cvt_pk_bf16_f32 v25, v42, v43
	v_add_u32_e32 v12, 0xb0, v129
	v_lshrrev_b32_e32 v12, 2, v12
	v_mad_u64_u32 v[12:13], s[56:57], v12, s98, v[128:129]
	v_ashrrev_i32_e32 v13, 31, v12
	v_lshl_add_u64 v[16:17], v[12:13], 1, s[4:5]
	v_cvt_pk_bf16_f32 v12, v20, v21
	v_cvt_pk_bf16_f32 v13, v22, v23
	v_cvt_pk_bf16_f32 v14, v0, v1
	v_cvt_pk_bf16_f32 v15, v2, v3
	v_cvt_pk_bf16_f32 v0, v8, v9
	v_cvt_pk_bf16_f32 v1, v10, v11
	v_cvt_pk_bf16_f32 v2, v4, v5
	v_cvt_pk_bf16_f32 v3, v6, v7
	global_store_dwordx4 v[32:33], v[24:27], off
	global_store_dwordx4 v[16:17], v[12:15], off
	global_store_dwordx4 v[16:17], v[0:3], off offset:1024

; #define LAS __attribute__((address_space(3)))
; __device__ __forceinline__ unsigned cvt_pk_bf16(float lo, float hi) { f32x2_c v = {lo, hi}; bf16x2_c b = __builtin_convertvector(v, bf16x2_c); return __builtin_bit_cast(unsigned, b); }
; __global__ void __launch_bounds__(NWAVES * 64, 2) mk_fwd(Args args) {
;     ...
;                 for (int w2 = 0; w2 < 2; ++w2) { const LA& st = w2 ? sb : sa;
;                     float lt = st.l; { auto rr = __builtin_amdgcn_permlane32_swap(__float_as_uint(lt), __float_as_uint(lt), false, false); lt = __uint_as_float(rr[0]) + __uint_as_float(rr[1]); }
;                     const float inv = __builtin_amdgcn_rcpf(lt); const int rho = tl0 + 32 * w2 + r32;
;                     if (hi == 0) LSE1[rho] = st.m + __builtin_amdgcn_logf(lt);
; #pragma unroll
;                     for (int db = 0; db < 2; ++db)
; #pragma unroll
;                         for (int g = 0; g < 4; ++g) { const f32x16& o = db ? st.o1 : st.o0; u32x2 w; w.x = cvt_pk_bf16(o[4 * g] * inv, o[4 * g + 1] * inv); w.y = cvt_pk_bf16(o[4 * g + 2] * inv, o[4 * g + 3] * inv);
;                             *(LAS u32x2*)(O1 + o1_off(rho, 8 * db + 2 * g + hi)) = w; } }
;             }
;             {
;                 const int q0 = 64 * (v32 * 8 + wave), tqa = q0 + r32, tqb = tqa + 32, kvh = h >> 2;
;                 bf16x8 qa[4], qb[4]; const bf16_t* qp = PROJ + (size_t)tqa * PP + C_QA + h * 64 + 8 * hi;
; #pragma unroll
;                 for (int d0 = 0; d0 < 4; ++d0) { qa[d0] = *(const bf16x8*)(qp + 16 * d0); qb[d0] = *(const bf16x8*)(qp + (size_t)32 * PP + 16 * d0); }
;                 LA sa, sb; sa.o0 = zero16(); sa.o1 = sa.o0; sa.m = NEGBIG; sa.l = 0.f; sb.o0 = zero16(); sb.o1 = sb.o0; sb.m = NEGBIG; sb.l = 0.f;
;                 u32x2 za[8], zb[8]; la_loadz(za, PROJ + (size_t)tqa * PP + C_ZA + h * 64, hi); la_loadz(zb, PROJ + (size_t)tqb * PP + C_ZA + h * 64, hi);
;                 const int vd = kvh * 64 + r32; const unsigned kc = (unsigned)(C_KA + kvh * 64 + 8 * hi);
;                 const VSG vs{(const char*)VTA};
.LBB0_671:
	s_or_b64 exec, exec, s[6:7]
	v_rcp_f32_e32 v34, v33
	v_lshrrev_b32_e32 v33, 1, v32
	v_lshrrev_b32_e32 v35, 4, v32
	v_add_u32_e32 v33, v33, v184
	v_add_lshl_u32 v33, v33, v35, 3
	v_lshl_add_u32 v32, v32, 7, 0
	v_pk_mul_f32 v[0:1], v[34:35], v[0:1] op_sel_hi:[0,1]
	v_pk_mul_f32 v[2:3], v[34:35], v[2:3] op_sel_hi:[0,1]
	v_and_b32_e32 v35, 0x78, v33
	v_cvt_pk_bf16_f32 v0, v0, v1
	v_cvt_pk_bf16_f32 v1, v2, v3
	v_add_u32_e32 v2, v32, v35
	ds_write_b64 v2, v[0:1] offset:36864
	v_pk_mul_f32 v[0:1], v[34:35], v[4:5] op_sel_hi:[0,1]
	v_pk_mul_f32 v[2:3], v[34:35], v[6:7] op_sel_hi:[0,1]
	v_cvt_pk_bf16_f32 v0, v0, v1
	v_cvt_pk_bf16_f32 v1, v2, v3
	v_add_u32_e32 v2, 16, v33
	v_and_b32_e32 v2, 0x78, v2
	v_add_u32_e32 v2, v32, v2
	ds_write_b64 v2, v[0:1] offset:36864
	v_pk_mul_f32 v[0:1], v[34:35], v[8:9] op_sel_hi:[0,1]
	v_pk_mul_f32 v[2:3], v[34:35], v[10:11] op_sel_hi:[0,1]
	v_cvt_pk_bf16_f32 v0, v0, v1
	v_cvt_pk_bf16_f32 v1, v2, v3
	v_add_u32_e32 v2, 32, v33
	v_and_b32_e32 v2, 0x78, v2
	v_add_u32_e32 v2, v32, v2
	ds_write_b64 v2, v[0:1] offset:36864
	v_pk_mul_f32 v[0:1], v[34:35], v[12:13] op_sel_hi:[0,1]
	v_pk_mul_f32 v[2:3], v[34:35], v[14:15] op_sel_hi:[0,1]
	v_cvt_pk_bf16_f32 v0, v0, v1
	v_cvt_pk_bf16_f32 v1, v2, v3
	v_add_u32_e32 v2, 48, v33
	v_and_b32_e32 v2, 0x78, v2
	v_add_u32_e32 v2, v32, v2
	ds_write_b64 v2, v[0:1] offset:36864
	v_pk_mul_f32 v[0:1], v[34:35], v[16:17] op_sel_hi:[0,1]
	v_pk_mul_f32 v[2:3], v[34:35], v[18:19] op_sel_hi:[0,1]
	v_cvt_pk_bf16_f32 v0, v0, v1
	v_cvt_pk_bf16_f32 v1, v2, v3
	v_xad_u32 v2, v35, 64, v32
	ds_write_b64 v2, v[0:1] offset:36864
	v_pk_mul_f32 v[0:1], v[34:35], v[20:21] op_sel_hi:[0,1]
	v_pk_mul_f32 v[2:3], v[34:35], v[22:23] op_sel_hi:[0,1]
	v_cvt_pk_bf16_f32 v0, v0, v1
	v_cvt_pk_bf16_f32 v1, v2, v3
	v_add_u32_e32 v2, 0x50, v33
	v_and_b32_e32 v2, 0x78, v2
	v_add_u32_e32 v2, v32, v2
	ds_write_b64 v2, v[0:1] offset:36864
	v_pk_mul_f32 v[0:1], v[34:35], v[24:25] op_sel_hi:[0,1]
	v_pk_mul_f32 v[2:3], v[34:35], v[26:27] op_sel_hi:[0,1]
	v_cvt_pk_bf16_f32 v0, v0, v1
	v_cvt_pk_bf16_f32 v1, v2, v3
	v_add_u32_e32 v2, 0x60, v33
	v_and_b32_e32 v2, 0x78, v2
	v_add_u32_e32 v2, v32, v2
	s_add_u32 s6, s34, 0x1a400000
	ds_write_b64 v2, v[0:1] offset:36864
	v_pk_mul_f32 v[0:1], v[34:35], v[28:29] op_sel_hi:[0,1]
	v_pk_mul_f32 v[2:3], v[34:35], v[30:31] op_sel_hi:[0,1]
	s_addc_u32 s7, s35, 0
	s_ashr_i32 s40, s58, 6
	v_cvt_pk_bf16_f32 v0, v0, v1
	v_cvt_pk_bf16_f32 v1, v2, v3
	v_add_u32_e32 v2, 0x70, v33
	s_lshl_b32 s10, s0, 3
	v_and_b32_e32 v2, 0x78, v2
	s_add_i32 s8, s10, s40
	v_add_u32_e32 v2, v32, v2
	s_lshl_b32 s11, s8, 6
	ds_write_b64 v2, v[0:1] offset:36864
	v_or_b32_e32 v182, s11, v186
	v_mov_b64_e32 v[2:3], s[74:75]
	v_mad_i64_i32 v[0:1], s[8:9], v182, s64, v[2:3]
	s_lshl_b64 s[70:71], s[30:31], 1
	v_lshl_add_u64 v[4:5], v[0:1], 0, s[70:71]
	v_lshlrev_b32_e32 v188, 1, v146
	v_lshl_add_u64 v[0:1], v[4:5], 0, v[188:189]
	s_mov_b32 s8, 0x69000
	v_or_b32_e32 v164, 32, v182
	v_add_co_u32_e32 v6, vcc, s8, v0
	v_mad_i64_i32 v[2:3], s[8:9], v164, s64, v[2:3]
	s_ashr_i32 s8, s37, 1
	s_andn2_b32 s8, s8, 63
	s_add_i32 s9, s8, 0x200
	v_mov_b32_e32 v147, v189
	v_lshl_add_u64 v[2:3], v[2:3], 0, s[70:71]
	v_or_b32_e32 v192, s9, v146
	s_add_i32 s9, s11, 0xffffff80
	v_lshl_add_u64 v[4:5], v[4:5], 0, v[146:147]
	v_lshl_add_u64 v[2:3], v[2:3], 0, v[146:147]
	s_cmpk_lt_u32 s9, 0x4000
	v_addc_co_u32_e32 v7, vcc, 0, v1, vcc
	global_load_dwordx4 v[80:83], v[0:1], off
	global_load_dwordx4 v[84:87], v[0:1], off offset:32
	global_load_dwordx4 v[88:91], v[6:7], off
	global_load_dwordx4 v[92:95], v[6:7], off offset:32
	global_load_dwordx4 v[96:99], v[0:1], off offset:64
	global_load_dwordx4 v[100:103], v[0:1], off offset:96
	global_load_dwordx4 v[104:107], v[6:7], off offset:64
	global_load_dwordx4 v[108:111], v[6:7], off offset:96
	v_mov_b32 v32, 0
	v_mov_b32 v0, 0
	global_load_dwordx2 v[144:145], v[4:5], off offset:1536
	global_load_dwordx2 v[178:179], v[4:5], off offset:1552
	global_load_dwordx2 v[176:177], v[4:5], off offset:1568
	global_load_dwordx2 v[174:175], v[4:5], off offset:1584
	global_load_dwordx2 v[172:173], v[4:5], off offset:1600
	global_load_dwordx2 v[170:171], v[4:5], off offset:1616
	global_load_dwordx2 v[168:169], v[4:5], off offset:1632
	global_load_dwordx2 v[166:167], v[4:5], off offset:1648
	global_load_dwordx2 v[162:163], v[2:3], off offset:1536
	global_load_dwordx2 v[160:161], v[2:3], off offset:1552
	global_load_dwordx2 v[158:159], v[2:3], off offset:1568
	global_load_dwordx2 v[156:157], v[2:3], off offset:1584
	global_load_dwordx2 v[154:155], v[2:3], off offset:1600
	global_load_dwordx2 v[152:153], v[2:3], off offset:1616
	global_load_dwordx2 v[150:151], v[2:3], off offset:1632
	global_load_dwordx2 v[148:149], v[2:3], off offset:1648
	s_cselect_b32 s9, s9, s11
	v_or_b32_e32 v1, s9, v185
	v_mul_lo_u32 v1, v1, s67
	v_add_lshl_u32 v1, v1, v192, 1
	global_load_dwordx4 v[124:127], v1, s[74:75]
	global_load_dwordx4 v[120:123], v1, s[74:75] offset:32
	global_load_dwordx4 v[116:119], v1, s[74:75] offset:64
	global_load_dwordx4 v[112:115], v1, s[74:75] offset:96
	v_or_b32_e32 v16, s8, v186
	v_lshrrev_b32_e32 v16, 1, v16
	v_mul_lo_u32 v16, v16, s65
	v_lshlrev_b32_e32 v18, 5, v186
	v_mov_b32_e32 v46, v32
	v_mov_b32_e32 v47, v32
	v_mov_b32_e32 v14, v0
	v_mov_b32_e32 v15, v0
	v_lshl_add_u32 v17, s9, 1, v16
	v_and_b32_e32 v147, 32, v18
	v_mov_b32_e32 v33, v32
	v_mov_b32_e32 v34, v32
	v_mov_b32_e32 v35, v32
	v_mov_b32_e32 v36, v32
	v_mov_b32_e32 v37, v32
	v_mov_b32_e32 v38, v32
	v_mov_b32_e32 v39, v32
	v_mov_b32_e32 v40, v32
	v_mov_b32_e32 v41, v32
	v_mov_b32_e32 v42, v32
	v_mov_b32_e32 v43, v32
	v_mov_b32_e32 v44, v32
; template <class MB> __device__ __forceinline__ void la_soft(LA& st, f32x16& s, const TP& t, bf16x8& pf0, bf16x8& pf1) {
;     ...
;     float rs = 0.f;
; #pragma unroll
;     for (int r = 0; r < 16; ++r) { s[r] = __builtin_amdgcn_exp2f(s[r] - st.m); rs += s[r]; }
;     st.l += rs;
;     u32x4 p0, p1;
; #pragma unroll
;     for (int e = 0; e < 4; ++e) { p0[e] = cvt_pk_bf16(s[2 * e], s[2 * e + 1]); p1[e] = cvt_pk_bf16(s[8 + 2 * e], s[8 + 2 * e + 1]); }
;     pf0 = __builtin_bit_cast(bf16x8, p0); pf1 = __builtin_bit_cast(bf16x8, p1);
; }
; template <class MB, int V1, class VS> __device__ __forceinline__ void la_step2(LA& sa, LA& sb, const bf16x8 (&qa)[4], const bf16x8 (&qb)[4], Frag& f, const char* kb, const VS& vs, const TP& t, const TP& n) {
;     bf16x8 pa0, pa1;
;     { f32x16 s0 = zero16();
; #pragma unroll
;       for (int d0 = 0; d0 < 4; ++d0) s0 = __builtin_amdgcn_mfma_f32_32x32x16_bf16(f.k[d0], qa[d0], s0, 0, 0, 0);
;       la_soft<MB>(sa, s0, t, pa0, pa1); }
;     f32x16 s1 = zero16();
; #pragma unroll
;     for (int d0 = 0; d0 < 4; ++d0) s1 = __builtin_amdgcn_mfma_f32_32x32x16_bf16(f.k[d0], qb[d0], s1, 0, 0, 0);
;     la_loadK(f, kb, n);
;     sa.o0 = __builtin_amdgcn_mfma_f32_32x32x16_bf16(f.v[0], pa0, sa.o0, 0, 0, 0); sa.o1 = __builtin_amdgcn_mfma_f32_32x32x16_bf16(f.v[2], pa0, sa.o1, 0, 0, 0);
;     sa.o0 = __builtin_amdgcn_mfma_f32_32x32x16_bf16(f.v[1], pa1, sa.o0, 0, 0, 0); sa.o1 = __builtin_amdgcn_mfma_f32_32x32x16_bf16(f.v[3], pa1, sa.o1, 0, 0, 0);
;     { bf16x8 pb0, pb1; const TP tb = MB::second(t);
;       la_soft<MB>(sb, s1, tb, pb0, pb1);
;       sb.o0 = __builtin_amdgcn_mfma_f32_32x32x16_bf16(f.v[0], pb0, sb.o0, 0, 0, 0); sb.o1 = __builtin_amdgcn_mfma_f32_32x32x16_bf16(f.v[2], pb0, sb.o1, 0, 0, 0);
; __global__ void __launch_bounds__(NWAVES * 64, 2) mk_fwd(Args args) {
;     ...
;                 auto tile = [&](int i) -> TP { const int t0r = q0 - 128 + 32 * i; const bool ok = t0r >= 0 && t0r < SEQ; const int t0 = ok ? t0r : q0; TP t;
;                     t.koff = ((unsigned)(t0 + lam) * PP + kc) * 2u; t.voff = (unsigned)(vt_off(vd, t0 + 8 * hi) * 2);
;                     t.tp = (ok && i <= 8) ? (const LAS char*)(tabA + (TABA_C + t0 + 8 * hi - tqa)) : negp;
;                     t.tp2 = (ok && i >= 1) ? (const LAS char*)(tabA + (TABA_C + t0 + 8 * hi - tqb)) : negp; t.cb = 0; return t; };
;                 LA_RUN2(10, tile, MB_A, 32, PB, vs);
	v_mov_b32_e32 v45, v32
	v_mov_b32_e32 v1, v0
	v_mov_b32_e32 v2, v0
	v_mov_b32_e32 v3, v0
	v_mov_b32_e32 v4, v0
	v_mov_b32_e32 v5, v0
	v_mov_b32_e32 v6, v0
	v_mov_b32_e32 v7, v0
	v_mov_b32_e32 v8, v0
	v_mov_b32_e32 v9, v0
	v_mov_b32_e32 v10, v0
	v_mov_b32_e32 v11, v0
	v_mov_b32_e32 v12, v0
	v_mov_b32_e32 v13, v0
	s_mov_b32 s98, 0x10080
	v_or_b32_e32 v227, s8, v186
	v_lshrrev_b32_e32 v227, 2, v227
	v_mul_lo_u32 v227, v227, s98
	v_lshlrev_b32_e32 v228, 3, v186
	v_and_b32_e32 v228, 24, v228
	v_lshl_or_b32 v228, v146, 2, v228
	v_or_b32_e32 v194, v227, v228
	v_lshl_add_u32 v73, s9, 2, v194
	v_mov_b64_e32 v[62:63], v[46:47]
	v_mov_b64_e32 v[30:31], v[14:15]
	v_ashrrev_i32_e32 v183, 31, v182
	s_mov_b32 s12, 0
	v_lshlrev_b32_e32 v180, 2, v184
	v_ashrrev_i32_e32 v165, 31, v164
	s_movk_i32 s13, 0xff80
	v_add_u32_e32 v195, 0, v190
	v_mov_b32_e32 v196, 0xf149f2ca
	v_mov_b32_e32 v193, 0
	v_mov_b64_e32 v[60:61], v[44:45]
	v_mov_b64_e32 v[58:59], v[42:43]
	v_mov_b64_e32 v[56:57], v[40:41]
	v_mov_b64_e32 v[54:55], v[38:39]
	v_mov_b64_e32 v[52:53], v[36:37]
	v_mov_b64_e32 v[50:51], v[34:35]
	v_mov_b64_e32 v[48:49], v[32:33]
	v_mov_b32_e32 v190, 0
	v_mov_b32_e32 v191, 0xf149f2ca
	v_mov_b64_e32 v[28:29], v[12:13]
	v_mov_b64_e32 v[26:27], v[10:11]
	v_mov_b64_e32 v[24:25], v[8:9]
	v_mov_b64_e32 v[22:23], v[6:7]
	v_mov_b64_e32 v[20:21], v[4:5]
	v_mov_b64_e32 v[18:19], v[2:3]
	v_mov_b64_e32 v[16:17], v[0:1]
	s_branch .LBB0_673
.LBB0_672:
	v_add_f32_e32 v73, 0, v199
	v_add_f32_e32 v73, v198, v73
	v_add_f32_e32 v73, v201, v73
	v_add_f32_e32 v73, v200, v73
	v_add_f32_e32 v73, v203, v73
	v_add_f32_e32 v73, v202, v73
	v_add_f32_e32 v73, v205, v73
	v_add_f32_e32 v73, v204, v73
	v_add_f32_e32 v73, v207, v73
	v_add_f32_e32 v73, v206, v73
	v_add_f32_e32 v73, v211, v73
	v_add_f32_e32 v73, v210, v73
	v_add_f32_e32 v73, v209, v73
	v_add_f32_e32 v73, v208, v73
	v_add_f32_e32 v73, v213, v73
	v_add_f32_e32 v73, v212, v73
	v_add_f32_e32 v193, v193, v73
	v_sub_f32_e32 v73, v219, v191
	v_exp_f32_e32 v74, v73
	v_sub_f32_e32 v73, v218, v191
	v_exp_f32_e32 v75, v73
	v_sub_f32_e32 v77, v216, v191
	v_exp_f32_e32 v77, v77
	v_sub_f32_e32 v78, v215, v191
	v_exp_f32_e32 v78, v78
	v_sub_f32_e32 v79, v214, v191
	v_add_f32_e32 v76, 0, v74
	v_exp_f32_e32 v79, v79
	v_sub_f32_e32 v197, v197, v191
	v_add_f32_e32 v76, v75, v76
	v_exp_f32_e32 v197, v197
	v_sub_f32_e32 v69, v69, v191
	v_add_f32_e32 v76, v77, v76
	v_exp_f32_e32 v198, v69
	v_sub_f32_e32 v68, v68, v191
	v_add_f32_e32 v76, v78, v76
	v_exp_f32_e32 v199, v68
	v_sub_f32_e32 v68, v217, v191
	v_add_f32_e32 v76, v79, v76
	v_exp_f32_e32 v200, v68
	v_sub_f32_e32 v68, v72, v191
	v_add_f32_e32 v76, v197, v76
	v_exp_f32_e32 v72, v68
	v_add_f32_e32 v68, v198, v76
	v_add_f32_e32 v68, v199, v68
	v_add_f32_e32 v68, v200, v68
	v_add_f32_e32 v76, v72, v68
	v_sub_f32_e32 v68, v71, v191
	v_exp_f32_e32 v201, v68
	v_sub_f32_e32 v68, v70, v191
	v_exp_f32_e32 v202, v68
	v_cvt_pk_bf16_f32 v68, v74, v75
	v_cvt_pk_bf16_f32 v69, v77, v78
	v_cvt_pk_bf16_f32 v70, v79, v197
	v_cvt_pk_bf16_f32 v71, v198, v199
	v_sub_f32_e32 v65, v65, v191
	v_add_f32_e32 v74, v201, v76
	v_mfma_f32_32x32x16_bf16 v[16:31], v[140:143], v[68:71], v[16:31]
	v_sub_f32_e32 v67, v67, v191
	v_exp_f32_e32 v76, v65
	v_sub_f32_e32 v65, v66, v191
	v_sub_f32_e32 v64, v64, v191
	v_exp_f32_e32 v75, v67
	v_add_f32_e32 v74, v202, v74
	s_lshl_b32 s8, s8, 2
	v_mfma_f32_32x32x16_bf16 v[0:15], v[136:139], v[68:71], v[0:15]
	v_exp_f32_e32 v68, v65
	v_exp_f32_e32 v69, v64
	v_cvt_pk_bf16_f32 v64, v200, v72
	v_cvt_pk_bf16_f32 v65, v201, v202
	v_cvt_pk_bf16_f32 v66, v75, v76
	v_cvt_pk_bf16_f32 v67, v68, v69
	v_add_f32_e32 v70, v75, v74
	v_add_f32_e32 v70, v76, v70
	v_mfma_f32_32x32x16_bf16 v[16:31], v[132:135], v[64:67], v[16:31]
	v_add_f32_e32 v68, v68, v70
	s_andn2_b32 s8, s8, 0x7f
	v_add_f32_e32 v68, v69, v68
	s_addk_i32 s12, 0x80
	v_add_u32_e32 v73, s8, v194
	v_add_f32_e32 v190, v190, v68
	s_cmpk_eq_i32 s12, 0x500
	v_mfma_f32_32x32x16_bf16 v[0:15], v[128:131], v[64:67], v[0:15]
	s_cbranch_scc1 .LBB0_677
; template <class MB> __device__ __forceinline__ void la_soft(LA& st, f32x16& s, const TP& t, bf16x8& pf0, bf16x8& pf1) {
;     float mx = NEGBIG;
; #pragma unroll
;     for (int r = 0; r < 16; ++r) { s[r] = MB::apply(t, r, s[r]); mx = __builtin_fmaxf(mx, s[r]); }
;     { auto rr = __builtin_amdgcn_permlane32_swap(__float_as_uint(mx), __float_as_uint(mx), false, false); mx = __builtin_fmaxf(__uint_as_float(rr[0]), __uint_as_float(rr[1])); }
;     if (__any(mx > st.m)) { const float mn = __builtin_fmaxf(st.m, mx), alpha = __builtin_amdgcn_exp2f(st.m - mn); st.m = mn; st.l *= alpha; st.o0 *= alpha; st.o1 *= alpha; }
; template <class MB, int V1, class VS> __device__ __forceinline__ void la_step2(LA& sa, LA& sb, const bf16x8 (&qa)[4], const bf16x8 (&qb)[4], Frag& f, const char* kb, const VS& vs, const TP& t, const TP& n) {
;     bf16x8 pa0, pa1;
;     { f32x16 s0 = zero16();
; #pragma unroll
;       for (int d0 = 0; d0 < 4; ++d0) s0 = __builtin_amdgcn_mfma_f32_32x32x16_bf16(f.k[d0], qa[d0], s0, 0, 0, 0);
;       la_soft<MB>(sa, s0, t, pa0, pa1); }
.LBB0_673:
	v_lshlrev_b32_e32 v64, 1, v73
	v_ashrrev_i32_e32 v65, 31, v64
	v_lshl_add_u64 v[64:65], s[6:7], 0, v[64:65]
	v_add_co_u32_e32 v66, vcc, s80, v64
	s_add_i32 s8, s11, s13
	s_nop 0
	v_addc_co_u32_e32 v67, vcc, 0, v65, vcc
	global_load_dwordx4 v[128:131], v[66:67], off offset:2176
	global_load_dwordx4 v[136:139], v[66:67], off offset:2048
	global_load_dwordx4 v[132:135], v[64:65], off offset:128
	global_load_dwordx4 v[140:143], v[64:65], off
	s_cmpk_lt_u32 s8, 0x4000
	s_cselect_b64 s[8:9], -1, 0
	s_cmpk_lg_i32 s12, 0x480
	s_cselect_b64 s[14:15], -1, 0
	v_add_u32_e32 v197, s12, v195
	s_and_b64 vcc, s[14:15], s[8:9]
	v_add_u32_e32 v64, 0x80, v197
	v_mov_b32_e32 v65, s53
	v_cndmask_b32_e32 v212, v65, v64, vcc
	v_mov_b32 v64, 0
	ds_read2_b32 v[200:201], v212 offset1:1
	v_mov_b32_e32 v65, v64
	v_mov_b32_e32 v66, v64
	v_mov_b32_e32 v67, v64
	v_mov_b32_e32 v68, v64
	v_mov_b32_e32 v69, v64
	v_mov_b32_e32 v70, v64
	v_mov_b32_e32 v71, v64
	v_mov_b32_e32 v72, v64
	v_mov_b32_e32 v73, v64
	v_mov_b32_e32 v74, v64
	v_mov_b32_e32 v75, v64
	v_mov_b32_e32 v76, v64
	v_mov_b32_e32 v77, v64
	v_mov_b32_e32 v78, v64
	v_mov_b32_e32 v79, v64
	s_waitcnt vmcnt(7)
	s_nop 0
	v_mfma_f32_32x32x16_bf16 v[64:79], v[124:127], v[80:83], v[64:79]
	s_waitcnt vmcnt(6)
	v_mfma_f32_32x32x16_bf16 v[64:79], v[120:123], v[84:87], v[64:79]
	s_waitcnt vmcnt(5)
	v_mfma_f32_32x32x16_bf16 v[64:79], v[116:119], v[96:99], v[64:79]
	s_waitcnt vmcnt(4)
	v_mfma_f32_32x32x16_bf16 v[64:79], v[112:115], v[100:103], v[64:79]
	s_waitcnt lgkmcnt(0)
	s_nop 10
	v_add_f32_e32 v199, v64, v200
	v_add_f32_e32 v198, v65, v201
	ds_read2_b32 v[64:65], v212 offset0:2 offset1:3
	v_max3_f32 v202, v199, s2, v198
	s_waitcnt lgkmcnt(0)
	v_add_f32_e32 v201, v66, v64
	v_add_f32_e32 v200, v67, v65
	ds_read2_b32 v[64:65], v212 offset0:4 offset1:5
	v_max3_f32 v66, v202, v201, v200
	s_waitcnt lgkmcnt(0)
	v_add_f32_e32 v203, v68, v64
	v_add_f32_e32 v202, v69, v65
	ds_read2_b32 v[64:65], v212 offset0:6 offset1:7
	v_max3_f32 v66, v66, v203, v202
	s_waitcnt lgkmcnt(0)
	v_add_f32_e32 v205, v70, v64
	v_add_f32_e32 v204, v71, v65
	ds_read2_b32 v[64:65], v212 offset0:16 offset1:17
	v_max3_f32 v66, v66, v205, v204
	s_waitcnt lgkmcnt(0)
	v_add_f32_e32 v207, v72, v64
	v_add_f32_e32 v206, v73, v65
	ds_read2_b32 v[64:65], v212 offset0:18 offset1:19
	v_max3_f32 v66, v66, v207, v206
	s_waitcnt lgkmcnt(0)
	v_add_f32_e32 v211, v74, v64
	v_add_f32_e32 v210, v75, v65
	ds_read2_b32 v[64:65], v212 offset0:20 offset1:21
	v_max3_f32 v66, v66, v211, v210
	s_waitcnt lgkmcnt(0)
	v_add_f32_e32 v209, v76, v64
	v_add_f32_e32 v208, v77, v65
	ds_read2_b32 v[64:65], v212 offset0:22 offset1:23
	v_max3_f32 v66, v66, v209, v208
	s_waitcnt lgkmcnt(0)
	v_add_f32_e32 v213, v78, v64
	v_add_f32_e32 v212, v79, v65
	v_max3_f32 v64, v66, v213, v212
	v_mov_b32_e32 v65, v64
	s_nop 1
	v_permlane32_swap_b32_e32 v64, v65
	v_max_f32_e32 v65, v65, v65
	v_max_f32_e32 v64, v64, v64
	v_max_f32_e32 v64, v64, v65
	v_cmp_gt_f32_e32 vcc, v64, v196
	s_cbranch_vccz .LBB0_675
	v_max_f32_e32 v64, v64, v64
	v_max_f32_e32 v65, v196, v196
	v_max_f32_e32 v65, v65, v64
	v_sub_f32_e32 v64, v196, v65
	v_exp_f32_e32 v64, v64
	v_mov_b32_e32 v196, v65
	v_mul_f32_e32 v193, v193, v64
	v_pk_mul_f32 v[62:63], v[62:63], v[64:65] op_sel_hi:[1,0]
	v_pk_mul_f32 v[60:61], v[60:61], v[64:65] op_sel_hi:[1,0]
	v_pk_mul_f32 v[58:59], v[58:59], v[64:65] op_sel_hi:[1,0]
	v_pk_mul_f32 v[56:57], v[56:57], v[64:65] op_sel_hi:[1,0]
	v_pk_mul_f32 v[54:55], v[54:55], v[64:65] op_sel_hi:[1,0]
	v_pk_mul_f32 v[52:53], v[52:53], v[64:65] op_sel_hi:[1,0]
	v_pk_mul_f32 v[50:51], v[50:51], v[64:65] op_sel_hi:[1,0]
	v_pk_mul_f32 v[48:49], v[48:49], v[64:65] op_sel_hi:[1,0]
	v_pk_mul_f32 v[46:47], v[46:47], v[64:65] op_sel_hi:[1,0]
	v_pk_mul_f32 v[44:45], v[44:45], v[64:65] op_sel_hi:[1,0]
	v_pk_mul_f32 v[42:43], v[42:43], v[64:65] op_sel_hi:[1,0]
	v_pk_mul_f32 v[40:41], v[40:41], v[64:65] op_sel_hi:[1,0]
	v_pk_mul_f32 v[38:39], v[38:39], v[64:65] op_sel_hi:[1,0]
	v_pk_mul_f32 v[36:37], v[36:37], v[64:65] op_sel_hi:[1,0]
	v_pk_mul_f32 v[34:35], v[34:35], v[64:65] op_sel_hi:[1,0]
	v_pk_mul_f32 v[32:33], v[32:33], v[64:65] op_sel_hi:[1,0]

; __global__ void __launch_bounds__(NWAVES * 64, 2) mk_fwd(Args args) {
	.amdhsa_kernel _Z6mk_fwd4Args
		.amdhsa_group_segment_fixed_size 0
		.amdhsa_private_segment_fixed_size 0
		.amdhsa_kernarg_size 384
		.amdhsa_user_sgpr_count 2
		.amdhsa_user_sgpr_dispatch_ptr 0
		.amdhsa_user_sgpr_queue_ptr 0
		.amdhsa_user_sgpr_kernarg_segment_ptr 1
		.amdhsa_user_sgpr_dispatch_id 0
		.amdhsa_user_sgpr_kernarg_preload_length 0
		.amdhsa_user_sgpr_kernarg_preload_offset 0
		.amdhsa_user_sgpr_private_segment_size 0
		.amdhsa_uses_dynamic_stack 0
		.amdhsa_enable_private_segment 0
		.amdhsa_system_sgpr_workgroup_id_x 1
		.amdhsa_system_sgpr_workgroup_id_y 0
		.amdhsa_system_sgpr_workgroup_id_z 0
		.amdhsa_system_sgpr_workgroup_info 0
		.amdhsa_system_vgpr_workitem_id 2
		.amdhsa_next_free_vgpr 256
		.amdhsa_next_free_sgpr 102
		.amdhsa_accum_offset 256
		.amdhsa_reserve_vcc 1
		.amdhsa_float_round_mode_32 0
		.amdhsa_float_round_mode_16_64 0
		.amdhsa_float_denorm_mode_32 3
		.amdhsa_float_denorm_mode_16_64 3
		.amdhsa_dx10_clamp 1
		.amdhsa_ieee_mode 1
		.amdhsa_fp16_overflow 0
		.amdhsa_tg_split 0
		.amdhsa_exception_fp_ieee_invalid_op 0
		.amdhsa_exception_fp_denorm_src 0
		.amdhsa_exception_fp_ieee_div_zero 0
		.amdhsa_exception_fp_ieee_overflow 0
		.amdhsa_exception_fp_ieee_underflow 0
		.amdhsa_exception_fp_ieee_inexact 0
		.amdhsa_exception_int_div_zero 0
	.end_amdhsa_kernel

; __global__ void __launch_bounds__(NWAVES * 64, 2) mk_fwd(Args args) {
amdhsa.kernels:
  - .agpr_count:     0
    .args:
      - .offset:         0
        .size:           128
        .value_kind:     by_value
      - .offset:         128
        .size:           4
        .value_kind:     hidden_block_count_x
      - .offset:         132
        .size:           4
        .value_kind:     hidden_block_count_y
      - .offset:         136
        .size:           4
        .value_kind:     hidden_block_count_z
      - .offset:         140
        .size:           2
        .value_kind:     hidden_group_size_x
      - .offset:         142
        .size:           2
        .value_kind:     hidden_group_size_y
      - .offset:         144
        .size:           2
        .value_kind:     hidden_group_size_z
      - .offset:         146
        .size:           2
        .value_kind:     hidden_remainder_x
      - .offset:         148
        .size:           2
        .value_kind:     hidden_remainder_y
      - .offset:         150
        .size:           2
        .value_kind:     hidden_remainder_z
      - .offset:         168
        .size:           8
        .value_kind:     hidden_global_offset_x
      - .offset:         176
        .size:           8
        .value_kind:     hidden_global_offset_y
      - .offset:         184
        .size:           8
        .value_kind:     hidden_global_offset_z
      - .offset:         192
        .size:           2
        .value_kind:     hidden_grid_dims
      - .offset:         216
        .size:           8
        .value_kind:     hidden_multigrid_sync_arg
      - .offset:         248
        .size:           4
        .value_kind:     hidden_dynamic_lds_size
    .group_segment_fixed_size: 0
    .kernarg_segment_align: 8
    .kernarg_segment_size: 384
    .language:       OpenCL C
    .language_version:
      - 2
      - 0
    .max_flat_workgroup_size: 512
    .name:           _Z6mk_fwd4Args
    .private_segment_fixed_size: 0
    .sgpr_count:     108
    .sgpr_spill_count: 60
    .symbol:         _Z6mk_fwd4Args.kd
    .uniform_work_group_size: 1
    .uses_dynamic_stack: false
    .vgpr_count:     256
    .vgpr_spill_count: 0
    .wavefront_size: 64
